# m25 + step A: first head accumulates with v_fma(...,0) instead of zeroing the eight sums, and the level-1 histogram address uses five instead of six VALU per key (per-lane row offset pre-shifted into
# speedup vs baseline: 1.0067x; 1.0031x over previous
.Lidx_pw0:
	v_cndmask_b32_e64 v19, 0, 1, s[78:79]
	v_cmp_ne_u32_e64 s[28:29], 1, v19
	s_andn2_b64 vcc, exec, s[78:79]
	v_lshlrev_b32_e32 v39, 4, v36
	v_lshlrev_b32_e32 v172, 2, v167
	v_lshl_add_u32 v40, v167, 13, 0
	v_lshl_add_u32 v41, v18, 2, s14
	s_waitcnt lgkmcnt(0)
	s_barrier
	s_cbranch_vccnz .LBB0_1383
	s_add_i32 s0, s77, 8
	s_lshr_b32 s1, s0, 29
	s_add_i32 s0, s0, s1
	s_ashr_i32 s13, s0, 3
	s_add_i32 s0, 0, 0x22200
	v_add_u32_e32 v173, s0, v39
	v_readlane_b32 s0, v251, 29
	s_add_i32 s14, s13, -2
	s_add_i32 s15, s13, -3
	v_add_u32_e32 v174, s0, v39
	s_max_i32 s0, s13, 2
	s_lshl_b32 s0, s0, 3
	s_add_i32 s0, s0, -8
	s_and_b32 s16, s0, -16
	v_or_b32_e32 v175, s24, v167
	s_add_i32 s16, s16, 16
	s_mov_b32 s17, 0
	v_mov_b64_e32 v[42:43], 0
	v_mov_b64_e32 v[44:45], 0
	v_mov_b64_e32 v[46:47], 0
	v_mov_b64_e32 v[48:49], 0
	v_mov_b64_e32 v[50:51], 0
	v_mov_b64_e32 v[52:53], 0
	v_mov_b64_e32 v[54:55], 0
	v_mov_b64_e32 v[56:57], 0
	v_mov_b64_e32 v[58:59], 0
	v_mov_b64_e32 v[60:61], 0
	v_mov_b64_e32 v[62:63], 0
	v_mov_b64_e32 v[64:65], 0
	v_mov_b64_e32 v[66:67], 0
	v_mov_b64_e32 v[68:69], 0
	v_mov_b64_e32 v[70:71], 0
	v_mov_b64_e32 v[72:73], 0
	v_mov_b64_e32 v[74:75], 0
	v_mov_b64_e32 v[76:77], 0
	v_mov_b64_e32 v[78:79], 0
	v_mov_b64_e32 v[80:81], 0
	v_mov_b64_e32 v[82:83], 0
	v_mov_b64_e32 v[84:85], 0
	v_mov_b64_e32 v[86:87], 0
	v_mov_b64_e32 v[88:89], 0
	v_mov_b64_e32 v[90:91], 0
	v_mov_b64_e32 v[92:93], 0
	v_mov_b64_e32 v[94:95], 0
	v_mov_b64_e32 v[96:97], 0
	v_mov_b64_e32 v[98:99], 0
	v_mov_b64_e32 v[100:101], 0
	v_mov_b64_e32 v[102:103], 0
	v_mov_b64_e32 v[104:105], 0
	v_mov_b64_e32 v[106:107], 0
	v_mov_b64_e32 v[108:109], 0
	v_mov_b64_e32 v[110:111], 0
	v_mov_b64_e32 v[112:113], 0
	v_mov_b64_e32 v[114:115], 0
	v_mov_b32_e32 v117, 0
	v_mov_b64_e32 v[118:119], 0
	v_mov_b64_e32 v[120:121], 0
	v_mov_b64_e32 v[122:123], 0
	v_mov_b64_e32 v[124:125], 0
	v_mov_b64_e32 v[126:127], 0
	v_mov_b64_e32 v[128:129], 0
	v_mov_b64_e32 v[130:131], 0
	v_mov_b64_e32 v[132:133], 0
	v_mov_b64_e32 v[134:135], 0
	v_mov_b64_e32 v[136:137], 0
	v_mov_b64_e32 v[138:139], 0
	v_mov_b64_e32 v[140:141], 0
	v_mov_b64_e32 v[142:143], 0
	v_mov_b64_e32 v[144:145], 0
	v_mov_b64_e32 v[146:147], 0
	v_mov_b64_e32 v[148:149], 0
	v_mov_b64_e32 v[150:151], 0
	v_mov_b64_e32 v[152:153], 0
	v_mov_b64_e32 v[154:155], 0
	v_mov_b64_e32 v[156:157], 0
	v_mov_b64_e32 v[158:159], 0
	v_mov_b64_e32 v[160:161], 0
	v_mov_b64_e32 v[162:163], 0
	v_mov_b64_e32 v[164:165], 0
	v_mov_b32_e32 v166, 0
	v_mov_b64_e32 v[168:169], 0
	v_mov_b64_e32 v[170:171], 0
	v_mov_b32_e32 v176, v41
	s_mov_b32 s18, 0
	s_mov_b32 s19, 0
	v_lshlrev_b32_e32 v246, 21, v172
	s_branch .LBB0_1296

.LBB0_1296:
	s_add_i32 s8, s3, s17
	s_add_i32 s0, s18, 1
	s_add_i32 s9, s8, 8
	s_cmp_lt_i32 s0, s13
	s_cselect_b64 s[0:1], -1, 0
	s_and_b64 vcc, s[0:1], exec
	s_cselect_b32 s10, s9, s8
	s_add_i32 s9, s8, 16
	s_cmp_lt_i32 s18, s14
	s_cselect_b32 s9, s9, s8
	s_add_i32 s8, s8, 24
	s_cmp_lt_i32 s18, s15
	s_cselect_b32 s11, s8, s9
	s_lshl_b32 s68, s9, 4
	s_lshl_b64 s[8:9], s[68:69], 7
	ds_read_b128 v[200:203], v173
	ds_read_b128 v[204:207], v173 offset:1024
	ds_read_b128 v[22:25], v174
	ds_read_b128 v[18:21], v174 offset:1024
	ds_read_b128 v[208:211], v173 offset:2048
	ds_read_b128 v[212:215], v173 offset:3072
	ds_read_b128 v[216:219], v173 offset:4096
	ds_read_b128 v[226:229], v173 offset:5120
	s_waitcnt vmcnt(0) lgkmcnt(6)
	v_mfma_f32_16x16x32_bf16 v[230:233], v[6:9], v[200:203], 0
	ds_read_b128 v[178:181], v173 offset:6144
	ds_read_b128 v[182:185], v173 offset:7168
	v_mfma_f32_16x16x32_bf16 v[234:237], v[14:17], v[200:203], 0
	v_mfma_f32_16x16x32_bf16 v[230:233], v[2:5], v[204:207], v[230:233]
	s_nop 3
	v_mfma_f32_16x16x32_bf16 v[234:237], v[10:13], v[204:207], v[234:237]
	s_waitcnt lgkmcnt(4)
	v_mfma_f32_16x16x32_bf16 v[238:241], v[6:9], v[208:211], 0
	ds_read_b128 v[200:203], v173 offset:8192
	ds_read_b128 v[204:207], v173 offset:9216
	v_max_i32_e32 v250, 0, v230
	v_fma_f32 v34, v250, v22, 0
	v_max_i32_e32 v225, 0, v231
	v_fma_f32 v35, v225, v22, 0
	v_mfma_f32_16x16x32_bf16 v[242:245], v[14:17], v[208:211], 0
	v_max_i32_e32 v250, 0, v232
	v_fma_f32 v32, v250, v22, 0
	v_max_i32_e32 v225, 0, v233
	v_fma_f32 v33, v225, v22, 0
	v_mfma_f32_16x16x32_bf16 v[238:241], v[2:5], v[212:215], v[238:241]
	v_max_i32_e32 v250, 0, v234
	v_fma_f32 v30, v250, v22, 0
	v_max_i32_e32 v225, 0, v235
	v_fma_f32 v31, v225, v22, 0
	v_mfma_f32_16x16x32_bf16 v[242:245], v[10:13], v[212:215], v[242:245]
	v_max_i32_e32 v250, 0, v236
	v_fma_f32 v28, v250, v22, 0
	v_max_i32_e32 v225, 0, v237
	v_fma_f32 v29, v225, v22, 0
	s_waitcnt lgkmcnt(4)
	v_mfma_f32_16x16x32_bf16 v[230:233], v[6:9], v[216:219], 0
	ds_read_b128 v[208:211], v173 offset:10240
	ds_read_b128 v[212:215], v173 offset:11264
	v_max_i32_e32 v250, 0, v238
	v_fmac_f32_e32 v34, v250, v23
	v_max_i32_e32 v225, 0, v239
	v_fmac_f32_e32 v35, v225, v23
	v_mfma_f32_16x16x32_bf16 v[234:237], v[14:17], v[216:219], 0
	v_max_i32_e32 v250, 0, v240
	v_fmac_f32_e32 v32, v250, v23
	v_max_i32_e32 v225, 0, v241
	v_fmac_f32_e32 v33, v225, v23
	v_mfma_f32_16x16x32_bf16 v[230:233], v[2:5], v[226:229], v[230:233]
	v_max_i32_e32 v250, 0, v242
	v_fmac_f32_e32 v30, v250, v23
	v_max_i32_e32 v225, 0, v243
	v_fmac_f32_e32 v31, v225, v23
	v_mfma_f32_16x16x32_bf16 v[234:237], v[10:13], v[226:229], v[234:237]
	v_max_i32_e32 v250, 0, v244
	v_fmac_f32_e32 v28, v250, v23
	v_max_i32_e32 v225, 0, v245
	v_fmac_f32_e32 v29, v225, v23
	s_waitcnt lgkmcnt(4)
	v_mfma_f32_16x16x32_bf16 v[238:241], v[6:9], v[178:181], 0
	ds_read_b128 v[216:219], v173 offset:12288
	ds_read_b128 v[226:229], v173 offset:13312
	v_max_i32_e32 v250, 0, v230
	v_fmac_f32_e32 v34, v250, v24
	v_max_i32_e32 v225, 0, v231
	v_fmac_f32_e32 v35, v225, v24
	v_mfma_f32_16x16x32_bf16 v[242:245], v[14:17], v[178:181], 0
	v_max_i32_e32 v250, 0, v232
	v_fmac_f32_e32 v32, v250, v24
	v_max_i32_e32 v225, 0, v233
	v_fmac_f32_e32 v33, v225, v24
	v_mfma_f32_16x16x32_bf16 v[238:241], v[2:5], v[182:185], v[238:241]
	v_max_i32_e32 v250, 0, v234
	v_fmac_f32_e32 v30, v250, v24
	v_max_i32_e32 v225, 0, v235
	v_fmac_f32_e32 v31, v225, v24
	v_mfma_f32_16x16x32_bf16 v[242:245], v[10:13], v[182:185], v[242:245]
	v_max_i32_e32 v250, 0, v236
	v_fmac_f32_e32 v28, v250, v24
	v_max_i32_e32 v225, 0, v237
	v_fmac_f32_e32 v29, v225, v24
	s_waitcnt lgkmcnt(4)
	v_mfma_f32_16x16x32_bf16 v[230:233], v[6:9], v[200:203], 0
	ds_read_b128 v[178:181], v173 offset:14336
	ds_read_b128 v[182:185], v173 offset:15360
	v_max_i32_e32 v250, 0, v238
	v_fmac_f32_e32 v34, v250, v25
	v_max_i32_e32 v225, 0, v239
	v_fmac_f32_e32 v35, v225, v25
	v_mfma_f32_16x16x32_bf16 v[234:237], v[14:17], v[200:203], 0
	v_max_i32_e32 v250, 0, v240
	v_fmac_f32_e32 v32, v250, v25
	v_max_i32_e32 v225, 0, v241
	v_fmac_f32_e32 v33, v225, v25
	v_mfma_f32_16x16x32_bf16 v[230:233], v[2:5], v[204:207], v[230:233]
	v_max_i32_e32 v250, 0, v242
	v_fmac_f32_e32 v30, v250, v25
	v_max_i32_e32 v225, 0, v243
	v_fmac_f32_e32 v31, v225, v25
	v_mfma_f32_16x16x32_bf16 v[234:237], v[10:13], v[204:207], v[234:237]
	v_max_i32_e32 v250, 0, v244
	v_fmac_f32_e32 v28, v250, v25
	v_max_i32_e32 v225, 0, v245
	v_fmac_f32_e32 v29, v225, v25
	s_waitcnt lgkmcnt(4)
	v_mfma_f32_16x16x32_bf16 v[238:241], v[6:9], v[208:211], 0
	v_max_i32_e32 v250, 0, v230
	v_fmac_f32_e32 v34, v250, v18
	v_max_i32_e32 v225, 0, v231
	v_fmac_f32_e32 v35, v225, v18
	v_mfma_f32_16x16x32_bf16 v[242:245], v[14:17], v[208:211], 0
	v_max_i32_e32 v250, 0, v232
	v_fmac_f32_e32 v32, v250, v18
	v_max_i32_e32 v225, 0, v233
	v_fmac_f32_e32 v33, v225, v18
	v_mfma_f32_16x16x32_bf16 v[238:241], v[2:5], v[212:215], v[238:241]
	v_max_i32_e32 v250, 0, v234
	v_fmac_f32_e32 v30, v250, v18
	v_max_i32_e32 v225, 0, v235
	v_fmac_f32_e32 v31, v225, v18
	v_mfma_f32_16x16x32_bf16 v[242:245], v[10:13], v[212:215], v[242:245]
	v_max_i32_e32 v250, 0, v236
	v_fmac_f32_e32 v28, v250, v18
	v_max_i32_e32 v225, 0, v237
	v_fmac_f32_e32 v29, v225, v18
	s_waitcnt lgkmcnt(2)
	v_mfma_f32_16x16x32_bf16 v[230:233], v[6:9], v[216:219], 0
	v_max_i32_e32 v250, 0, v238
	v_fmac_f32_e32 v34, v250, v19
	v_max_i32_e32 v225, 0, v239
	v_fmac_f32_e32 v35, v225, v19
	v_mfma_f32_16x16x32_bf16 v[234:237], v[14:17], v[216:219], 0
	v_max_i32_e32 v250, 0, v240
	v_fmac_f32_e32 v32, v250, v19
	v_max_i32_e32 v225, 0, v241
	v_fmac_f32_e32 v33, v225, v19
	v_mfma_f32_16x16x32_bf16 v[230:233], v[2:5], v[226:229], v[230:233]
	v_max_i32_e32 v250, 0, v242
	v_fmac_f32_e32 v30, v250, v19
	v_max_i32_e32 v225, 0, v243
	v_fmac_f32_e32 v31, v225, v19
	v_mfma_f32_16x16x32_bf16 v[234:237], v[10:13], v[226:229], v[234:237]
	v_max_i32_e32 v250, 0, v244
	v_fmac_f32_e32 v28, v250, v19
	v_max_i32_e32 v225, 0, v245
	v_fmac_f32_e32 v29, v225, v19
	s_waitcnt lgkmcnt(0)
	v_mfma_f32_16x16x32_bf16 v[238:241], v[6:9], v[178:181], 0
	v_max_i32_e32 v250, 0, v230
	v_fmac_f32_e32 v34, v250, v20
	v_max_i32_e32 v225, 0, v231
	v_fmac_f32_e32 v35, v225, v20
	v_mfma_f32_16x16x32_bf16 v[242:245], v[14:17], v[178:181], 0
	v_max_i32_e32 v250, 0, v232
	v_fmac_f32_e32 v32, v250, v20
	v_max_i32_e32 v225, 0, v233
	v_fmac_f32_e32 v33, v225, v20
	v_mfma_f32_16x16x32_bf16 v[238:241], v[2:5], v[182:185], v[238:241]
	v_max_i32_e32 v250, 0, v234
	v_fmac_f32_e32 v30, v250, v20
	v_max_i32_e32 v225, 0, v235
	v_fmac_f32_e32 v31, v225, v20
	v_mfma_f32_16x16x32_bf16 v[242:245], v[10:13], v[182:185], v[242:245]
	v_max_i32_e32 v250, 0, v236
	v_fmac_f32_e32 v28, v250, v20
	v_max_i32_e32 v225, 0, v237
	v_fmac_f32_e32 v29, v225, v20
	v_max_i32_e32 v250, 0, v238
	v_fmac_f32_e32 v34, v250, v21
	v_max_i32_e32 v225, 0, v239
	v_fmac_f32_e32 v35, v225, v21
	v_max_i32_e32 v250, 0, v240
	v_fmac_f32_e32 v32, v250, v21
	v_max_i32_e32 v225, 0, v241
	v_fmac_f32_e32 v33, v225, v21
	v_max_i32_e32 v250, 0, v242
	v_fmac_f32_e32 v30, v250, v21
	v_max_i32_e32 v225, 0, v243
	v_fmac_f32_e32 v31, v225, v21
	v_max_i32_e32 v250, 0, v244
	v_fmac_f32_e32 v28, v250, v21
	v_max_i32_e32 v225, 0, v245
	v_fmac_f32_e32 v29, v225, v21
	v_lshl_add_u64 v[2:3], v[26:27], 0, s[8:9]
	s_lshl_b32 s8, s11, 4
	s_ashr_i32 s9, s8, 31
	s_lshl_b64 s[8:9], s[8:9], 7
	v_lshl_add_u64 v[10:11], v[26:27], 0, s[8:9]
	global_load_dwordx4 v[6:9], v[2:3], off
	s_nop 0
	global_load_dwordx4 v[2:5], v[2:3], off offset:64
	s_nop 0
	global_load_dwordx4 v[14:17], v[10:11], off
	s_nop 0
	global_load_dwordx4 v[10:13], v[10:11], off offset:64
	s_cmp_eq_u32 s10, s12
	v_ashrrev_i32_e32 v178, 31, v34
	s_cbranch_scc1 .LBB0_1317
	v_bitop3_b32 v18, v178, v34, s76 bitop3:0x36
	v_add_u32_e32 v19, v246, v18
	v_lshrrev_b32_e32 v20, 21, v19
	v_lshrrev_b32_e32 v19, 3, v20
	v_bitop3_b32 v19, v19, v20, 28 bitop3:0x6c
	v_lshl_add_u32 v19, v19, 2, v40
	ds_add_u32 v19, v186
	v_ashrrev_i32_e32 v19, 31, v35
	v_bitop3_b32 v19, v19, v35, s76 bitop3:0x36
	v_add_u32_e32 v20, v246, v19
	v_lshrrev_b32_e32 v21, 21, v20
	v_lshrrev_b32_e32 v20, 3, v21
	v_bitop3_b32 v20, v20, v21, 28 bitop3:0x6c
	v_lshl_add_u32 v20, v20, 2, v40
	ds_add_u32 v20, v186
	v_ashrrev_i32_e32 v20, 31, v32
	v_bitop3_b32 v20, v20, v32, s76 bitop3:0x36
	v_add_u32_e32 v21, v246, v20
	v_lshrrev_b32_e32 v22, 21, v21
	v_lshrrev_b32_e32 v21, 3, v22
	v_bitop3_b32 v21, v21, v22, 28 bitop3:0x6c
	v_lshl_add_u32 v21, v21, 2, v40
	ds_add_u32 v21, v186
	v_ashrrev_i32_e32 v21, 31, v33
	v_bitop3_b32 v23, v21, v33, s76 bitop3:0x36
	v_add_u32_e32 v21, v246, v23
	v_lshrrev_b32_e32 v22, 21, v21
	v_lshrrev_b32_e32 v21, 3, v22
	v_bitop3_b32 v21, v21, v22, 28 bitop3:0x6c
	v_lshl_add_u32 v21, v21, 2, v40
	ds_add_u32 v21, v186
	s_mov_b64 s[10:11], 0
	v_mov_b32_e32 v25, 0
	v_mov_b32_e32 v24, 0
	v_mov_b32_e32 v22, 0
	v_mov_b32_e32 v21, 0
	s_mov_b64 s[8:9], 0
	s_mov_b64 vcc, vcc
	s_cbranch_vccz .LBB0_1299
	v_ashrrev_i32_e32 v21, 31, v30
	v_bitop3_b32 v21, v21, v30, s76 bitop3:0x36
	v_add_u32_e32 v22, v246, v21
	v_lshrrev_b32_e32 v24, 21, v22
	v_lshrrev_b32_e32 v22, 3, v24
	v_bitop3_b32 v22, v22, v24, 28 bitop3:0x6c
	v_lshl_add_u32 v22, v22, 2, v40
	ds_add_u32 v22, v186
	v_ashrrev_i32_e32 v22, 31, v31
	v_bitop3_b32 v22, v22, v31, s76 bitop3:0x36
	v_add_u32_e32 v24, v246, v22
	v_lshrrev_b32_e32 v25, 21, v24
	v_lshrrev_b32_e32 v24, 3, v25
	v_bitop3_b32 v24, v24, v25, 28 bitop3:0x6c
	v_lshl_add_u32 v24, v24, 2, v40
	ds_add_u32 v24, v186
	v_ashrrev_i32_e32 v24, 31, v28
	v_bitop3_b32 v24, v24, v28, s76 bitop3:0x36
	v_add_u32_e32 v25, v246, v24
	v_lshrrev_b32_e32 v177, 21, v25
	v_lshrrev_b32_e32 v25, 3, v177
	v_bitop3_b32 v25, v25, v177, 28 bitop3:0x6c
	v_lshl_add_u32 v25, v25, 2, v40
	ds_add_u32 v25, v186
	v_ashrrev_i32_e32 v25, 31, v29
	v_bitop3_b32 v177, v25, v29, s76 bitop3:0x36
	s_mov_b64 s[8:9], -1
	v_mov_b32_e32 v25, v177

.LBB0_1319:
	v_add_u32_e32 v28, v246, v177
	v_lshrrev_b32_e32 v29, 21, v28
	v_lshrrev_b32_e32 v28, 3, v29
	v_bitop3_b32 v28, v28, v29, 28 bitop3:0x6c
	v_lshl_add_u32 v28, v28, 2, v40
	ds_add_u32 v28, v186
